# v48 plus one static s_setprio 1 at kernel entry for waves 4-7 (the second wave of each SIMD)
# speedup vs baseline: 1.0025x; 1.0025x over previous
; __device__ __forceinline__ void phase_init(const Params& p) {
;   const int tidx = threadIdx.x;
;   const long gt = blockIdx.x * 512L + tidx, gn = gridDim.x * 512L;
;   float* hmeta = (float*)(p.ws + OFF_HMETA);
;   for (long i = gt; i < 5 * 16 * DM; i += gn) hmeta[i] = p.in[2][i % (16 * DM)];
; __global__ void __launch_bounds__(512) mega(Params p) {
;   cg::grid_group grid = cg::this_grid();
;   phase_init(p);
;   Ctx c; c.out = p.out; c.ws = p.ws; c.wv = __builtin_amdgcn_readfirstlane((int)(threadIdx.x >> 6)); c.bid = blockIdx.x; c.nb = gridDim.x;
_Z4mega6Params:
	v_readfirstlane_b32 s100, v0
	s_bitcmp1_b32 s100, 8
	s_cbranch_scc0 .Lprio_skip
	s_setprio 1
.Lprio_skip:
	s_load_dwordx16 s[36:51], s[0:1], 0x0
	s_load_dwordx8 s[24:31], s[0:1], 0xc0
	s_load_dword s34, s[0:1], 0xe0
	s_mov_b32 s35, 0
	s_add_u32 s68, s0, 0xe0
	s_mov_b32 s3, s35
	s_addc_u32 s69, s1, 0
	s_lshl_b64 s[4:5], s[2:3], 9
	v_and_b32_e32 v2, 0x3ff, v0
	v_or_b32_e32 v6, s4, v2
	v_mov_b32_e32 v7, s5
	s_mov_b64 s[4:5], 0x14000
	v_mov_b32_e32 v5, 0
	s_waitcnt lgkmcnt(0)
	s_lshl_b64 s[70:71], s[34:35], 9
	v_cmp_gt_u64_e32 vcc, s[4:5], v[6:7]
	v_lshlrev_b32_e32 v4, 2, v2
	s_and_saveexec_b64 s[4:5], vcc
	s_cbranch_execz .LBB0_3
	s_lshl_b64 s[6:7], s[2:3], 11
	s_add_u32 s6, s30, s6
	s_addc_u32 s7, s31, s7
	v_lshl_add_u64 v[8:9], s[6:7], 0, v[4:5]
	s_mov_b64 s[6:7], 0x2611000
	v_lshl_add_u64 v[8:9], v[8:9], 0, s[6:7]
	s_lshl_b64 s[6:7], s[34:35], 11
	s_mov_b64 s[8:9], 0
	s_mov_b64 s[10:11], 0x13fff
	v_mov_b64_e32 v[10:11], v[6:7]
